# v48 plus: attention loop issues the next tile's first four K-fragment LDS reads right after the barrier (before the global loads and back-edge bookkeeping); running-sum add moved ahead of the barrier
# baseline (speedup 1.0000x reference)
; #define MFMA(a, b, c) __builtin_amdgcn_mfma_f32_32x32x16_bf16((a), (b), (c), 0, 0, 0)
; DI void attn_item(const Params& p, int seq, int hd, int qblk, char* smem, int tid_) {
;     ...
;   for (int kt = 0; kt < 32; kt++) {
;     const u16* sK = (const u16*)(smem + (kt & 1) * 45056);
;     const u16* sV = sK + 64 * 200;
;     f32x16 st[2];
; #pragma unroll
;     for (int kb2 = 0; kb2 < 2; kb2++)
; #pragma unroll
;       for (int i = 0; i < 16; i++) st[kb2][i] = 0.f;
;     ...
;     {
;       bf16x8 kfr[4];
; #pragma unroll
;       for (int f = 0; f < 4; f++) kfr[f] = KFRAG(f);
;       __builtin_amdgcn_sched_barrier(0);
; #pragma unroll
;       for (int f = 0; f < 24; f++) {
;         st[f / 12] = MFMA(kfr[f & 3], qf[f % 12], st[f / 12]);
;         if (f + 4 < 24) kfr[f & 3] = KFRAG(f + 4);
;         __builtin_amdgcn_sched_barrier(0);
;       }
;     }
;     bf16x8 vfr[4];
; #pragma unroll
;     for (int g = 0; g < 4; g++) vfr[g] = VFRAG(g);
;     float mx = st[0][0];
; #pragma unroll
;     for (int i = 1; i < 16; i++) mx = fmaxf(mx, st[0][i]);
; #pragma unroll
;     for (int i = 0; i < 16; i++) mx = fmaxf(mx, st[1][i]);
;     mx = fmaxf(mx, __shfl_xor(mx, 32));
;     if (__any((fmaxf(m, mx) - m) > 8.f)) {
;       const float mnew = fmaxf(m, mx);
;       const float alpha = __builtin_amdgcn_exp2f(m - mnew);
;       m = mnew;
;       lsum *= alpha;
; #pragma unroll
;       for (int db = 0; db < 4; db++)
; #pragma unroll
;         for (int i = 0; i < 16; i++) o[db][i] *= alpha;
;     }
.Lattn_top2:
	s_waitcnt vmcnt(16) lgkmcnt(3)
	v_mfma_f32_32x32x16_bf16 v[64:79], v[64:67], v[140:143], 0
	ds_read_b128 v[92:95], v200 offset:128
	s_waitcnt vmcnt(15) lgkmcnt(3)
	v_mfma_f32_32x32x16_bf16 v[64:79], v[80:83], v[136:139], v[64:79]
	ds_read_b128 v[80:83], v200 offset:160
	s_waitcnt vmcnt(14) lgkmcnt(3)
	v_mfma_f32_32x32x16_bf16 v[64:79], v[84:87], v[132:135], v[64:79]
	ds_read_b128 v[84:87], v200 offset:192
	s_waitcnt vmcnt(13) lgkmcnt(3)
	v_mfma_f32_32x32x16_bf16 v[64:79], v[88:91], v[128:131], v[64:79]
	ds_read_b128 v[88:91], v200 offset:224
	s_waitcnt vmcnt(12) lgkmcnt(3)
	v_mfma_f32_32x32x16_bf16 v[64:79], v[92:95], v[124:127], v[64:79]
	ds_read_b128 v[92:95], v200 offset:256
	s_waitcnt vmcnt(11) lgkmcnt(3)
	v_mfma_f32_32x32x16_bf16 v[64:79], v[80:83], v[120:123], v[64:79]
	ds_read_b128 v[80:83], v200 offset:288
	s_waitcnt vmcnt(10) lgkmcnt(3)
	v_mfma_f32_32x32x16_bf16 v[64:79], v[84:87], v[116:119], v[64:79]
	ds_read_b128 v[84:87], v200 offset:320
	s_waitcnt vmcnt(9) lgkmcnt(3)
	v_mfma_f32_32x32x16_bf16 v[64:79], v[88:91], v[112:115], v[64:79]
	ds_read_b128 v[88:91], v200 offset:352
	s_waitcnt vmcnt(8) lgkmcnt(3)
	v_mfma_f32_32x32x16_bf16 v[64:79], v[92:95], v[108:111], v[64:79]
	ds_read_b128 v[92:95], v200 offset:12800
	s_waitcnt vmcnt(7) lgkmcnt(3)
	v_mfma_f32_32x32x16_bf16 v[64:79], v[80:83], v[104:107], v[64:79]
	ds_read_b128 v[164:167], v200 offset:12832
	s_waitcnt vmcnt(6) lgkmcnt(3)
	v_mfma_f32_32x32x16_bf16 v[64:79], v[84:87], v[100:103], v[64:79]
	ds_read_b128 v[168:171], v200 offset:12864
	s_waitcnt vmcnt(5) lgkmcnt(3)
	v_mfma_f32_32x32x16_bf16 v[64:79], v[88:91], v[96:99], v[64:79]
	ds_read_b128 v[172:175], v200 offset:12896
	s_waitcnt lgkmcnt(3)
	v_mfma_f32_32x32x16_bf16 v[80:95], v[92:95], v[140:143], 0
	ds_read_b128 v[176:179], v200 offset:12928
	s_waitcnt lgkmcnt(3)
	v_mfma_f32_32x32x16_bf16 v[80:95], v[164:167], v[136:139], v[80:95]
	ds_read_b128 v[164:167], v200 offset:12960
	s_waitcnt lgkmcnt(3)
	v_mfma_f32_32x32x16_bf16 v[80:95], v[168:171], v[132:135], v[80:95]
	ds_read_b128 v[168:171], v200 offset:12992
	s_waitcnt lgkmcnt(3)
	v_mfma_f32_32x32x16_bf16 v[80:95], v[172:175], v[128:131], v[80:95]
	ds_read_b128 v[172:175], v200 offset:13024
	s_waitcnt lgkmcnt(3)
	v_mfma_f32_32x32x16_bf16 v[80:95], v[176:179], v[124:127], v[80:95]
	ds_read_b128 v[176:179], v200 offset:13056
	s_waitcnt lgkmcnt(3)
	v_mfma_f32_32x32x16_bf16 v[80:95], v[164:167], v[120:123], v[80:95]
	ds_read_b128 v[164:167], v200 offset:13088
	s_waitcnt lgkmcnt(3)
	v_mfma_f32_32x32x16_bf16 v[80:95], v[168:171], v[116:119], v[80:95]
	ds_read_b128 v[168:171], v200 offset:13120
	s_waitcnt lgkmcnt(3)
	v_mfma_f32_32x32x16_bf16 v[80:95], v[172:175], v[112:115], v[80:95]
	ds_read_b128 v[172:175], v200 offset:13152
	s_waitcnt lgkmcnt(3)
	v_mfma_f32_32x32x16_bf16 v[80:95], v[176:179], v[108:111], v[80:95]
	s_waitcnt lgkmcnt(2)
	v_mfma_f32_32x32x16_bf16 v[80:95], v[164:167], v[104:107], v[80:95]
	s_waitcnt lgkmcnt(1)
	v_mfma_f32_32x32x16_bf16 v[80:95], v[168:171], v[100:103], v[80:95]
	s_waitcnt lgkmcnt(0)
	v_mfma_f32_32x32x16_bf16 v[80:95], v[172:175], v[96:99], v[80:95]
	v_max_f32_e32 v165, v65, v65
	v_max_f32_e32 v166, v64, v64
	v_max_f32_e32 v165, v166, v165
	v_max3_f32 v165, v165, v66, v67
	v_max3_f32 v165, v165, v68, v69
	v_max3_f32 v165, v165, v70, v71
	v_max3_f32 v165, v165, v72, v73
	v_max3_f32 v165, v165, v74, v75
	v_max3_f32 v165, v165, v76, v77
	v_max3_f32 v165, v165, v78, v79
	s_nop 1
	v_max3_f32 v165, v165, v80, v81
	v_max3_f32 v165, v165, v82, v83
	v_max3_f32 v165, v165, v84, v85
	v_max3_f32 v165, v165, v86, v87
	v_max3_f32 v165, v165, v88, v89
	v_max3_f32 v165, v165, v90, v91
	v_max3_f32 v165, v165, v92, v93
	v_add_u32_e32 v164, v198, v195
	v_max3_f32 v198, v165, v94, v95
	ds_bpermute_b32 v200, v183, v198
	ds_read_b128 v[176:179], v164 offset:25600
	ds_read_b128 v[172:175], v164 offset:30208
	ds_read_b128 v[168:171], v164 offset:34816
	ds_read_b128 v[164:167], v164 offset:39424
	s_waitcnt lgkmcnt(4)
	v_max3_f32 v198, v199, v198, v200
	v_sub_f32_e32 v200, v198, v199
	v_cmp_lt_f32_e32 vcc, s46, v200
	s_cbranch_vccz .LBB0_626
	v_sub_f32_e32 v199, v199, v198
	v_exp_f32_e32 v200, v199
	s_nop 0
	v_pk_mul_f32 v[62:63], v[62:63], v[200:201] op_sel_hi:[1,0]
	v_pk_mul_f32 v[60:61], v[60:61], v[200:201] op_sel_hi:[1,0]
	v_pk_mul_f32 v[58:59], v[58:59], v[200:201] op_sel_hi:[1,0]
	v_pk_mul_f32 v[56:57], v[56:57], v[200:201] op_sel_hi:[1,0]
	v_pk_mul_f32 v[54:55], v[54:55], v[200:201] op_sel_hi:[1,0]
	v_pk_mul_f32 v[52:53], v[52:53], v[200:201] op_sel_hi:[1,0]
	v_pk_mul_f32 v[50:51], v[50:51], v[200:201] op_sel_hi:[1,0]
	v_pk_mul_f32 v[48:49], v[48:49], v[200:201] op_sel_hi:[1,0]
	v_pk_mul_f32 v[46:47], v[46:47], v[200:201] op_sel_hi:[1,0]
	v_pk_mul_f32 v[44:45], v[44:45], v[200:201] op_sel_hi:[1,0]
	v_pk_mul_f32 v[42:43], v[42:43], v[200:201] op_sel_hi:[1,0]
	v_pk_mul_f32 v[40:41], v[40:41], v[200:201] op_sel_hi:[1,0]
	v_pk_mul_f32 v[38:39], v[38:39], v[200:201] op_sel_hi:[1,0]
	v_pk_mul_f32 v[36:37], v[36:37], v[200:201] op_sel_hi:[1,0]
	v_pk_mul_f32 v[34:35], v[34:35], v[200:201] op_sel_hi:[1,0]
	v_pk_mul_f32 v[32:33], v[32:33], v[200:201] op_sel_hi:[1,0]
	v_pk_mul_f32 v[30:31], v[30:31], v[200:201] op_sel_hi:[1,0]
	v_pk_mul_f32 v[28:29], v[28:29], v[200:201] op_sel_hi:[1,0]
	v_pk_mul_f32 v[26:27], v[26:27], v[200:201] op_sel_hi:[1,0]
	v_pk_mul_f32 v[24:25], v[24:25], v[200:201] op_sel_hi:[1,0]
	v_pk_mul_f32 v[22:23], v[22:23], v[200:201] op_sel_hi:[1,0]
	v_pk_mul_f32 v[20:21], v[20:21], v[200:201] op_sel_hi:[1,0]
	v_pk_mul_f32 v[18:19], v[18:19], v[200:201] op_sel_hi:[1,0]
	v_pk_mul_f32 v[16:17], v[16:17], v[200:201] op_sel_hi:[1,0]
	v_pk_mul_f32 v[14:15], v[14:15], v[200:201] op_sel_hi:[1,0]
	v_pk_mul_f32 v[12:13], v[12:13], v[200:201] op_sel_hi:[1,0]
	v_pk_mul_f32 v[10:11], v[10:11], v[200:201] op_sel_hi:[1,0]
	v_pk_mul_f32 v[8:9], v[8:9], v[200:201] op_sel_hi:[1,0]
	v_pk_mul_f32 v[6:7], v[6:7], v[200:201] op_sel_hi:[1,0]
	v_pk_mul_f32 v[4:5], v[4:5], v[200:201] op_sel_hi:[1,0]
	v_pk_mul_f32 v[2:3], v[2:3], v[200:201] op_sel_hi:[1,0]
	v_pk_mul_f32 v[0:1], v[0:1], v[200:201] op_sel_hi:[1,0]
	v_mul_f32_e32 v194, v194, v200
	s_branch .LBB0_627

; #define MFMA(a, b, c) __builtin_amdgcn_mfma_f32_32x32x16_bf16((a), (b), (c), 0, 0, 0)
; DI void attn_item(const Params& p, int seq, int hd, int qblk, char* smem, int tid_) {
;     ...
;     float ps = 0.f;
; #pragma unroll
;     for (int kb2 = 0; kb2 < 2; kb2++)
; #pragma unroll
;       for (int i = 0; i < 16; i++) {
;         float pv = __builtin_amdgcn_exp2f(st[kb2][i] - m);
;         st[kb2][i] = pv;
;         ps += pv;
;       }
;     lsum += ps;
;     __builtin_amdgcn_sched_barrier(0);
; #pragma unroll
;     for (int g = 0; g < 16; g++) {
;       const int kb2 = g >> 3, c = (g >> 2) & 1;
;       unsigned pk[4];
; #pragma unroll
;       for (int j = 0; j < 4; j++) pk[j] = pack2(st[kb2][8 * c + 2 * j], st[kb2][8 * c + 2 * j + 1]);
;       u32x4 pu = {pk[0], pk[1], pk[2], pk[3]};
;       bf16x8 pf = __builtin_bit_cast(bf16x8, pu);
;       o[g & 3] = MFMA(vfr[g & 3], pf, o[g & 3]);
;       if (g + 4 < 16) vfr[g & 3] = VFRAG(g + 4);
;       __builtin_amdgcn_sched_barrier(0);
;     }
;     ...
;     if (kt + 1 < 32) {
;       u16* sKn = (u16*)(smem + ((kt + 1) & 1) * 45056);
;       u16* sVn = sKn + 64 * 200;
; #pragma unroll
;       for (int i = 0; i < 3; i++) *(u32x4*)(sKn + kl + 64 * i) = rk[i];
; #pragma unroll
;       for (int i = 0; i < 2; i++) *(u32x4*)(sVn + vl + 64 * i * 72) = rv[i];
;     }
;     __syncthreads();
;     if (kt + 2 < 32) {
; #pragma unroll
;       for (int i = 0; i < 3; i++) rk[i] = *(const u32x4*)(kg + (size_t)(kt + 2) * 64 * 768 + 64 * i);
; #pragma unroll
;       for (int i = 0; i < 2; i++) rv[i] = *(const u32x4*)(vg + (size_t)(64 * i) * 2048 + (kt + 2) * 64);
;     }
.LBB0_627:
	v_sub_f32_e32 v64, v64, v198
	v_sub_f32_e32 v65, v65, v198
	v_sub_f32_e32 v66, v66, v198
	v_sub_f32_e32 v67, v67, v198
	v_sub_f32_e32 v68, v68, v198
	v_sub_f32_e32 v69, v69, v198
	v_sub_f32_e32 v70, v70, v198
	v_sub_f32_e32 v71, v71, v198
	v_sub_f32_e32 v72, v72, v198
	v_sub_f32_e32 v73, v73, v198
	v_sub_f32_e32 v74, v74, v198
	v_sub_f32_e32 v75, v75, v198
	v_sub_f32_e32 v76, v76, v198
	v_sub_f32_e32 v77, v77, v198
	v_sub_f32_e32 v78, v78, v198
	v_sub_f32_e32 v79, v79, v198
	v_sub_f32_e32 v80, v80, v198
	v_sub_f32_e32 v81, v81, v198
	v_sub_f32_e32 v82, v82, v198
	v_sub_f32_e32 v83, v83, v198
	v_sub_f32_e32 v84, v84, v198
	v_sub_f32_e32 v85, v85, v198
	v_sub_f32_e32 v86, v86, v198
	v_sub_f32_e32 v87, v87, v198
	v_sub_f32_e32 v88, v88, v198
	v_sub_f32_e32 v89, v89, v198
	v_sub_f32_e32 v90, v90, v198
	v_sub_f32_e32 v91, v91, v198
	v_sub_f32_e32 v92, v92, v198
	v_sub_f32_e32 v93, v93, v198
	v_sub_f32_e32 v94, v94, v198
	v_sub_f32_e32 v95, v95, v198
	v_exp_f32_e32 v64, v64
	v_exp_f32_e32 v65, v65
	v_exp_f32_e32 v66, v66
	v_exp_f32_e32 v67, v67
	v_exp_f32_e32 v68, v68
	v_exp_f32_e32 v69, v69
	v_exp_f32_e32 v70, v70
	v_exp_f32_e32 v71, v71
	v_exp_f32_e32 v72, v72
	v_exp_f32_e32 v73, v73
	v_exp_f32_e32 v74, v74
	v_exp_f32_e32 v75, v75
	v_exp_f32_e32 v76, v76
	v_exp_f32_e32 v77, v77
	v_exp_f32_e32 v78, v78
	v_exp_f32_e32 v79, v79
	v_exp_f32_e32 v80, v80
	v_exp_f32_e32 v81, v81
	v_exp_f32_e32 v82, v82
	v_exp_f32_e32 v83, v83
	v_exp_f32_e32 v84, v84
	v_exp_f32_e32 v85, v85
	v_exp_f32_e32 v86, v86
	v_exp_f32_e32 v87, v87
	v_exp_f32_e32 v88, v88
	v_exp_f32_e32 v89, v89
	v_exp_f32_e32 v90, v90
	v_exp_f32_e32 v91, v91
	v_exp_f32_e32 v92, v92
	v_exp_f32_e32 v93, v93
	v_exp_f32_e32 v94, v94
	v_exp_f32_e32 v95, v95
	v_cvt_pk_bf16_f32 v200, v64, v65
	v_cvt_pk_bf16_f32 v201, v66, v67
	v_cvt_pk_bf16_f32 v202, v68, v69
	v_cvt_pk_bf16_f32 v203, v70, v71
	v_add3_u32 v199, s5, v195, v188
	s_waitcnt lgkmcnt(3)
	v_mfma_f32_32x32x16_bf16 v[48:63], v[176:179], v[200:203], v[48:63]
	v_add_f32_e32 v64, 0, v64
	v_add_f32_e32 v64, v65, v64
	ds_read_b128 v[176:179], v199 offset:25632
	s_waitcnt lgkmcnt(3)
	v_mfma_f32_32x32x16_bf16 v[32:47], v[172:175], v[200:203], v[32:47]
	v_add_f32_e32 v64, v66, v64
	v_add_f32_e32 v64, v67, v64
	ds_read_b128 v[172:175], v199 offset:30240
	s_waitcnt lgkmcnt(3)
	v_mfma_f32_32x32x16_bf16 v[16:31], v[168:171], v[200:203], v[16:31]
	v_add_f32_e32 v64, v68, v64
	v_add_f32_e32 v64, v69, v64
	ds_read_b128 v[168:171], v199 offset:34848
	s_waitcnt lgkmcnt(3)
	v_mfma_f32_32x32x16_bf16 v[0:15], v[164:167], v[200:203], v[0:15]
	v_add_f32_e32 v64, v70, v64
	v_add_f32_e32 v64, v71, v64
	ds_read_b128 v[164:167], v199 offset:39456
	v_cvt_pk_bf16_f32 v200, v72, v73
	v_cvt_pk_bf16_f32 v201, v74, v75
	v_cvt_pk_bf16_f32 v202, v76, v77
	v_cvt_pk_bf16_f32 v203, v78, v79
	s_waitcnt lgkmcnt(3)
	s_nop 0
	v_mfma_f32_32x32x16_bf16 v[48:63], v[176:179], v[200:203], v[48:63]
	v_add_f32_e32 v64, v72, v64
	v_add_f32_e32 v64, v73, v64
	ds_read_b128 v[176:179], v199 offset:25664
	s_waitcnt lgkmcnt(3)
	v_mfma_f32_32x32x16_bf16 v[32:47], v[172:175], v[200:203], v[32:47]
	v_add_f32_e32 v64, v74, v64
	v_add_f32_e32 v64, v75, v64
	ds_read_b128 v[172:175], v199 offset:30272
	s_waitcnt lgkmcnt(3)
	v_mfma_f32_32x32x16_bf16 v[16:31], v[168:171], v[200:203], v[16:31]
	v_add_f32_e32 v64, v76, v64
	v_add_f32_e32 v64, v77, v64
	ds_read_b128 v[168:171], v199 offset:34880
	s_waitcnt lgkmcnt(3)
	v_mfma_f32_32x32x16_bf16 v[0:15], v[164:167], v[200:203], v[0:15]
	v_add_f32_e32 v64, v78, v64
	v_add_f32_e32 v64, v79, v64
	ds_read_b128 v[164:167], v199 offset:39488
	v_cvt_pk_bf16_f32 v200, v80, v81
	v_cvt_pk_bf16_f32 v201, v82, v83
	v_cvt_pk_bf16_f32 v202, v84, v85
	v_cvt_pk_bf16_f32 v203, v86, v87
	s_waitcnt lgkmcnt(3)
	s_nop 0
	v_mfma_f32_32x32x16_bf16 v[48:63], v[176:179], v[200:203], v[48:63]
	v_add_f32_e32 v64, v80, v64
	v_add_f32_e32 v64, v81, v64
	ds_read_b128 v[176:179], v199 offset:25696
	s_waitcnt lgkmcnt(3)
	v_mfma_f32_32x32x16_bf16 v[32:47], v[172:175], v[200:203], v[32:47]
	v_add_f32_e32 v64, v82, v64
	v_add_f32_e32 v64, v83, v64
	ds_read_b128 v[172:175], v199 offset:30304
	s_waitcnt lgkmcnt(3)
	v_mfma_f32_32x32x16_bf16 v[16:31], v[168:171], v[200:203], v[16:31]
	v_add_f32_e32 v64, v84, v64
	v_add_f32_e32 v64, v85, v64
	ds_read_b128 v[168:171], v199 offset:34912
	s_waitcnt lgkmcnt(3)
	v_mfma_f32_32x32x16_bf16 v[0:15], v[164:167], v[200:203], v[0:15]
	v_add_f32_e32 v64, v86, v64
	v_add_f32_e32 v64, v87, v64
	ds_read_b128 v[164:167], v199 offset:39520
	v_cvt_pk_bf16_f32 v200, v88, v89
	v_cvt_pk_bf16_f32 v201, v90, v91
	v_cvt_pk_bf16_f32 v202, v92, v93
	v_cvt_pk_bf16_f32 v203, v94, v95
	s_waitcnt lgkmcnt(3)
	s_nop 0
	v_mfma_f32_32x32x16_bf16 v[48:63], v[176:179], v[200:203], v[48:63]
	v_add_f32_e32 v64, v88, v64
	v_add_f32_e32 v64, v89, v64
	s_waitcnt lgkmcnt(2)
	v_mfma_f32_32x32x16_bf16 v[32:47], v[172:175], v[200:203], v[32:47]
	v_add_f32_e32 v64, v90, v64
	v_add_f32_e32 v64, v91, v64
	s_waitcnt lgkmcnt(1)
	v_mfma_f32_32x32x16_bf16 v[16:31], v[168:171], v[200:203], v[16:31]
	v_add_f32_e32 v64, v92, v64
	v_add_f32_e32 v64, v93, v64
	s_waitcnt lgkmcnt(0)
	v_mfma_f32_32x32x16_bf16 v[0:15], v[164:167], v[200:203], v[0:15]
	v_add_f32_e32 v64, v94, v64
	v_add_f32_e32 v64, v95, v64
	v_add_f32_e32 v194, v194, v64
	s_add_i32 s5, s3, 1
	s_bitcmp1_b32 s5, 0
	s_cselect_b32 s1, 0xb000, 0
	s_add_i32 s1, s1, 0
	v_lshl_add_u32 v164, v182, 1, s1
	s_waitcnt vmcnt(4)
	ds_write_b128 v164, v[144:147]
	s_waitcnt vmcnt(3)
	ds_write_b128 v164, v[148:151] offset:128
	s_waitcnt vmcnt(2)
	ds_write_b128 v164, v[152:155] offset:256
	v_lshl_add_u32 v164, v196, 1, s1
	s_cmp_gt_u32 s3, 29
	s_waitcnt vmcnt(1)
	ds_write_b128 v164, v[156:159] offset:25600
	s_waitcnt vmcnt(0)
	ds_write_b128 v164, v[160:163] offset:34816
	s_waitcnt lgkmcnt(0)
	s_barrier
	v_add3_u32 v200, s1, v188, v197
	ds_read_b128 v[64:67], v200
	ds_read_b128 v[80:83], v200 offset:32
	ds_read_b128 v[84:87], v200 offset:64
	ds_read_b128 v[88:91], v200 offset:96
	s_cbranch_scc1 .LBB0_629
	global_load_dwordx4 v[144:147], v[186:187], off offset:-128
	global_load_dwordx4 v[148:151], v[186:187], off
	global_load_dwordx4 v[152:155], v[186:187], off offset:128
	global_load_dwordx4 v[156:159], v[184:185], off
	v_add_co_u32_e32 v160, vcc, 0x40000, v184
	s_nop 1
	v_addc_co_u32_e32 v161, vcc, 0, v185, vcc
	global_load_dwordx4 v[160:163], v[160:161], off
.LBB0_629:
	s_mov_b64 s[6:7], 0x18000
	v_lshl_add_u64 v[184:185], v[184:185], 0, s[14:15]
	s_cmp_lg_u32 s5, 31
	v_lshl_add_u64 v[186:187], v[186:187], 0, s[6:7]
	s_cbranch_scc0 .LBB0_631
	v_mov_b32_e32 v199, v198
	s_mov_b32 s3, s5
	s_mov_b32 s5, s1
	v_add_u32_e32 v198, s5, v188
	s_branch .Lattn_top2
